# RWKV-7 prompt recurrence fully unrolled (16 steps, immediate LDS offsets, VOP3P dot2 with inline-0 acc; same f16/f32 arithmetic)
# speedup vs baseline: 1.0322x; 1.0322x over previous
.LBB0_1238:
	s_or_b64 exec, exec, s[18:19]
	s_waitcnt lgkmcnt(0)
	s_barrier
	ds_read_b128 v[72:75], v114 offset:41216
	ds_read_b128 v[68:71], v114 offset:45312
	ds_read_b128 v[64:67], v114 offset:49408
	ds_read_b128 v[56:59], v114 offset:53504
	ds_read_b128 v[60:63], v114 offset:28928
	ds_read_b32 v85, v115
	s_waitcnt lgkmcnt(0)
	v_dot2_f32_f16 v151, v127, v72, 0
	v_dot2_f32_f16 v151, v126, v73, v151
	v_dot2_f32_f16 v151, v125, v74, v151
	v_dot2_f32_f16 v151, v124, v75, v151
	ds_read_b128 v[134:137], v114 offset:41344
	ds_read_b128 v[138:141], v114 offset:45440
	ds_read_b128 v[142:145], v114 offset:49536
	v_add_f32_dpp v151, v151, v151 quad_perm:[1,0,3,2] row_mask:0xf bank_mask:0xf bound_ctrl:1
	ds_read_b128 v[130:133], v114 offset:29056
	ds_read_b128 v[146:149], v114 offset:53632
	v_add_f32_dpp v151, v151, v151 quad_perm:[2,3,0,1] row_mask:0xf bank_mask:0xf bound_ctrl:1
	ds_read_b32 v160, v115 offset:256
	s_nop 0
	v_add_f32_dpp v151, v151, v151 row_half_mirror row_mask:0xf bank_mask:0xf bound_ctrl:1
	v_cvt_pkrtz_f16_f32 v152, -v151, -v151
	v_pk_mul_f16 v153, v152, v68
	v_pk_mul_f16 v154, v152, v69
	v_pk_mul_f16 v155, v152, v70
	v_pk_mul_f16 v156, v152, v71
	v_pk_fma_f16 v153, v85, v64, v153
	v_pk_fma_f16 v154, v85, v65, v154
	v_pk_fma_f16 v155, v85, v66, v155
	v_pk_fma_f16 v156, v85, v67, v156
	v_pk_fma_f16 v127, v127, v60, v153
	v_pk_fma_f16 v126, v126, v61, v154
	v_pk_fma_f16 v125, v125, v62, v155
	v_pk_fma_f16 v124, v124, v63, v156
	v_dot2_f32_f16 v157, v127, v56, 0
	v_dot2_f32_f16 v157, v126, v57, v157
	v_dot2_f32_f16 v157, v125, v58, v157
	v_dot2_f32_f16 v157, v124, v59, v157
	s_waitcnt lgkmcnt(0)
	v_dot2_f32_f16 v151, v127, v134, 0
	v_dot2_f32_f16 v151, v126, v135, v151
	v_dot2_f32_f16 v151, v125, v136, v151
	v_dot2_f32_f16 v151, v124, v137, v151
	ds_read_b128 v[72:75], v114 offset:41472
	ds_read_b128 v[68:71], v114 offset:45568
	ds_read_b128 v[64:67], v114 offset:49664
	v_add_f32_dpp v151, v151, v151 quad_perm:[1,0,3,2] row_mask:0xf bank_mask:0xf bound_ctrl:1
	ds_read_b128 v[60:63], v114 offset:29184
	ds_read_b128 v[56:59], v114 offset:53760
	v_add_f32_dpp v151, v151, v151 quad_perm:[2,3,0,1] row_mask:0xf bank_mask:0xf bound_ctrl:1
	ds_read_b32 v85, v115 offset:512
	ds_write_b32 v116, v157 offset:0
	v_add_f32_dpp v151, v151, v151 row_half_mirror row_mask:0xf bank_mask:0xf bound_ctrl:1
	v_cvt_pkrtz_f16_f32 v152, -v151, -v151
	v_pk_mul_f16 v153, v152, v138
	v_pk_mul_f16 v154, v152, v139
	v_pk_mul_f16 v155, v152, v140
	v_pk_mul_f16 v156, v152, v141
	v_pk_fma_f16 v153, v160, v142, v153
	v_pk_fma_f16 v154, v160, v143, v154
	v_pk_fma_f16 v155, v160, v144, v155
	v_pk_fma_f16 v156, v160, v145, v156
	v_pk_fma_f16 v127, v127, v130, v153
	v_pk_fma_f16 v126, v126, v131, v154
	v_pk_fma_f16 v125, v125, v132, v155
	v_pk_fma_f16 v124, v124, v133, v156
	v_dot2_f32_f16 v158, v127, v146, 0
	v_dot2_f32_f16 v158, v126, v147, v158
	v_dot2_f32_f16 v158, v125, v148, v158
	v_dot2_f32_f16 v158, v124, v149, v158
	s_waitcnt lgkmcnt(0)
	v_dot2_f32_f16 v151, v127, v72, 0
	v_dot2_f32_f16 v151, v126, v73, v151
	v_dot2_f32_f16 v151, v125, v74, v151
	v_dot2_f32_f16 v151, v124, v75, v151
	ds_read_b128 v[134:137], v114 offset:41600
	ds_read_b128 v[138:141], v114 offset:45696
	ds_read_b128 v[142:145], v114 offset:49792
	v_add_f32_dpp v151, v151, v151 quad_perm:[1,0,3,2] row_mask:0xf bank_mask:0xf bound_ctrl:1
	ds_read_b128 v[130:133], v114 offset:29312
	ds_read_b128 v[146:149], v114 offset:53888
	v_add_f32_dpp v151, v151, v151 quad_perm:[2,3,0,1] row_mask:0xf bank_mask:0xf bound_ctrl:1
	ds_read_b32 v160, v115 offset:768
	ds_write_b32 v116, v158 offset:2048
	v_add_f32_dpp v151, v151, v151 row_half_mirror row_mask:0xf bank_mask:0xf bound_ctrl:1
	v_cvt_pkrtz_f16_f32 v152, -v151, -v151
	v_pk_mul_f16 v153, v152, v68
	v_pk_mul_f16 v154, v152, v69
	v_pk_mul_f16 v155, v152, v70
	v_pk_mul_f16 v156, v152, v71
	v_pk_fma_f16 v153, v85, v64, v153
	v_pk_fma_f16 v154, v85, v65, v154
	v_pk_fma_f16 v155, v85, v66, v155
	v_pk_fma_f16 v156, v85, v67, v156
	v_pk_fma_f16 v127, v127, v60, v153
	v_pk_fma_f16 v126, v126, v61, v154
	v_pk_fma_f16 v125, v125, v62, v155
	v_pk_fma_f16 v124, v124, v63, v156
	v_dot2_f32_f16 v157, v127, v56, 0
	v_dot2_f32_f16 v157, v126, v57, v157
	v_dot2_f32_f16 v157, v125, v58, v157
	v_dot2_f32_f16 v157, v124, v59, v157
	s_waitcnt lgkmcnt(0)
	v_dot2_f32_f16 v151, v127, v134, 0
	v_dot2_f32_f16 v151, v126, v135, v151
	v_dot2_f32_f16 v151, v125, v136, v151
	v_dot2_f32_f16 v151, v124, v137, v151
	ds_read_b128 v[72:75], v114 offset:41728
	ds_read_b128 v[68:71], v114 offset:45824
	ds_read_b128 v[64:67], v114 offset:49920
	v_add_f32_dpp v151, v151, v151 quad_perm:[1,0,3,2] row_mask:0xf bank_mask:0xf bound_ctrl:1
	ds_read_b128 v[60:63], v114 offset:29440
	ds_read_b128 v[56:59], v114 offset:54016
	v_add_f32_dpp v151, v151, v151 quad_perm:[2,3,0,1] row_mask:0xf bank_mask:0xf bound_ctrl:1
	ds_read_b32 v85, v115 offset:1024
	ds_write_b32 v116, v157 offset:4096
	v_add_f32_dpp v151, v151, v151 row_half_mirror row_mask:0xf bank_mask:0xf bound_ctrl:1
	v_cvt_pkrtz_f16_f32 v152, -v151, -v151
	v_pk_mul_f16 v153, v152, v138
	v_pk_mul_f16 v154, v152, v139
	v_pk_mul_f16 v155, v152, v140
	v_pk_mul_f16 v156, v152, v141
	v_pk_fma_f16 v153, v160, v142, v153
	v_pk_fma_f16 v154, v160, v143, v154
	v_pk_fma_f16 v155, v160, v144, v155
	v_pk_fma_f16 v156, v160, v145, v156
	v_pk_fma_f16 v127, v127, v130, v153
	v_pk_fma_f16 v126, v126, v131, v154
	v_pk_fma_f16 v125, v125, v132, v155
	v_pk_fma_f16 v124, v124, v133, v156
	v_dot2_f32_f16 v158, v127, v146, 0
	v_dot2_f32_f16 v158, v126, v147, v158
	v_dot2_f32_f16 v158, v125, v148, v158
	v_dot2_f32_f16 v158, v124, v149, v158
	s_waitcnt lgkmcnt(0)
	v_dot2_f32_f16 v151, v127, v72, 0
	v_dot2_f32_f16 v151, v126, v73, v151
	v_dot2_f32_f16 v151, v125, v74, v151
	v_dot2_f32_f16 v151, v124, v75, v151
	ds_read_b128 v[134:137], v114 offset:41856
	ds_read_b128 v[138:141], v114 offset:45952
	ds_read_b128 v[142:145], v114 offset:50048
	v_add_f32_dpp v151, v151, v151 quad_perm:[1,0,3,2] row_mask:0xf bank_mask:0xf bound_ctrl:1
	ds_read_b128 v[130:133], v114 offset:29568
	ds_read_b128 v[146:149], v114 offset:54144
	v_add_f32_dpp v151, v151, v151 quad_perm:[2,3,0,1] row_mask:0xf bank_mask:0xf bound_ctrl:1
	ds_read_b32 v160, v115 offset:1280
	ds_write_b32 v116, v158 offset:6144
	v_add_f32_dpp v151, v151, v151 row_half_mirror row_mask:0xf bank_mask:0xf bound_ctrl:1
	v_cvt_pkrtz_f16_f32 v152, -v151, -v151
	v_pk_mul_f16 v153, v152, v68
	v_pk_mul_f16 v154, v152, v69
	v_pk_mul_f16 v155, v152, v70
	v_pk_mul_f16 v156, v152, v71
	v_pk_fma_f16 v153, v85, v64, v153
	v_pk_fma_f16 v154, v85, v65, v154
	v_pk_fma_f16 v155, v85, v66, v155
	v_pk_fma_f16 v156, v85, v67, v156
	v_pk_fma_f16 v127, v127, v60, v153
	v_pk_fma_f16 v126, v126, v61, v154
	v_pk_fma_f16 v125, v125, v62, v155
	v_pk_fma_f16 v124, v124, v63, v156
	v_dot2_f32_f16 v157, v127, v56, 0
	v_dot2_f32_f16 v157, v126, v57, v157
	v_dot2_f32_f16 v157, v125, v58, v157
	v_dot2_f32_f16 v157, v124, v59, v157
	s_waitcnt lgkmcnt(0)
	v_dot2_f32_f16 v151, v127, v134, 0
	v_dot2_f32_f16 v151, v126, v135, v151
	v_dot2_f32_f16 v151, v125, v136, v151
	v_dot2_f32_f16 v151, v124, v137, v151
	ds_read_b128 v[72:75], v114 offset:41984
	ds_read_b128 v[68:71], v114 offset:46080
	ds_read_b128 v[64:67], v114 offset:50176
	v_add_f32_dpp v151, v151, v151 quad_perm:[1,0,3,2] row_mask:0xf bank_mask:0xf bound_ctrl:1
	ds_read_b128 v[60:63], v114 offset:29696
	ds_read_b128 v[56:59], v114 offset:54272
	v_add_f32_dpp v151, v151, v151 quad_perm:[2,3,0,1] row_mask:0xf bank_mask:0xf bound_ctrl:1
	ds_read_b32 v85, v115 offset:1536
	ds_write_b32 v116, v157 offset:8192
	v_add_f32_dpp v151, v151, v151 row_half_mirror row_mask:0xf bank_mask:0xf bound_ctrl:1
	v_cvt_pkrtz_f16_f32 v152, -v151, -v151
	v_pk_mul_f16 v153, v152, v138
	v_pk_mul_f16 v154, v152, v139
	v_pk_mul_f16 v155, v152, v140
	v_pk_mul_f16 v156, v152, v141
	v_pk_fma_f16 v153, v160, v142, v153
	v_pk_fma_f16 v154, v160, v143, v154
	v_pk_fma_f16 v155, v160, v144, v155
	v_pk_fma_f16 v156, v160, v145, v156
	v_pk_fma_f16 v127, v127, v130, v153
	v_pk_fma_f16 v126, v126, v131, v154
	v_pk_fma_f16 v125, v125, v132, v155
	v_pk_fma_f16 v124, v124, v133, v156
	v_dot2_f32_f16 v158, v127, v146, 0
	v_dot2_f32_f16 v158, v126, v147, v158
	v_dot2_f32_f16 v158, v125, v148, v158
	v_dot2_f32_f16 v158, v124, v149, v158
	s_waitcnt lgkmcnt(0)
	v_dot2_f32_f16 v151, v127, v72, 0
	v_dot2_f32_f16 v151, v126, v73, v151
	v_dot2_f32_f16 v151, v125, v74, v151
	v_dot2_f32_f16 v151, v124, v75, v151
	ds_read_b128 v[134:137], v114 offset:42112
	ds_read_b128 v[138:141], v114 offset:46208
	ds_read_b128 v[142:145], v114 offset:50304
	v_add_f32_dpp v151, v151, v151 quad_perm:[1,0,3,2] row_mask:0xf bank_mask:0xf bound_ctrl:1
	ds_read_b128 v[130:133], v114 offset:29824
	ds_read_b128 v[146:149], v114 offset:54400
	v_add_f32_dpp v151, v151, v151 quad_perm:[2,3,0,1] row_mask:0xf bank_mask:0xf bound_ctrl:1
	ds_read_b32 v160, v115 offset:1792
	ds_write_b32 v116, v158 offset:10240
	v_add_f32_dpp v151, v151, v151 row_half_mirror row_mask:0xf bank_mask:0xf bound_ctrl:1
	v_cvt_pkrtz_f16_f32 v152, -v151, -v151
	v_pk_mul_f16 v153, v152, v68
	v_pk_mul_f16 v154, v152, v69
	v_pk_mul_f16 v155, v152, v70
	v_pk_mul_f16 v156, v152, v71
	v_pk_fma_f16 v153, v85, v64, v153
	v_pk_fma_f16 v154, v85, v65, v154
	v_pk_fma_f16 v155, v85, v66, v155
	v_pk_fma_f16 v156, v85, v67, v156
	v_pk_fma_f16 v127, v127, v60, v153
	v_pk_fma_f16 v126, v126, v61, v154
	v_pk_fma_f16 v125, v125, v62, v155
	v_pk_fma_f16 v124, v124, v63, v156
	v_dot2_f32_f16 v157, v127, v56, 0
	v_dot2_f32_f16 v157, v126, v57, v157
	v_dot2_f32_f16 v157, v125, v58, v157
	v_dot2_f32_f16 v157, v124, v59, v157
	s_waitcnt lgkmcnt(0)
	v_dot2_f32_f16 v151, v127, v134, 0
	v_dot2_f32_f16 v151, v126, v135, v151
	v_dot2_f32_f16 v151, v125, v136, v151
	v_dot2_f32_f16 v151, v124, v137, v151
	ds_read_b128 v[72:75], v114 offset:42240
	ds_read_b128 v[68:71], v114 offset:46336
	ds_read_b128 v[64:67], v114 offset:50432
	v_add_f32_dpp v151, v151, v151 quad_perm:[1,0,3,2] row_mask:0xf bank_mask:0xf bound_ctrl:1
	ds_read_b128 v[60:63], v114 offset:29952
	ds_read_b128 v[56:59], v114 offset:54528
	v_add_f32_dpp v151, v151, v151 quad_perm:[2,3,0,1] row_mask:0xf bank_mask:0xf bound_ctrl:1
	ds_read_b32 v85, v115 offset:2048
	ds_write_b32 v116, v157 offset:12288
	v_add_f32_dpp v151, v151, v151 row_half_mirror row_mask:0xf bank_mask:0xf bound_ctrl:1
	v_cvt_pkrtz_f16_f32 v152, -v151, -v151
	v_pk_mul_f16 v153, v152, v138
	v_pk_mul_f16 v154, v152, v139
	v_pk_mul_f16 v155, v152, v140
	v_pk_mul_f16 v156, v152, v141
	v_pk_fma_f16 v153, v160, v142, v153
	v_pk_fma_f16 v154, v160, v143, v154
	v_pk_fma_f16 v155, v160, v144, v155
	v_pk_fma_f16 v156, v160, v145, v156
	v_pk_fma_f16 v127, v127, v130, v153
	v_pk_fma_f16 v126, v126, v131, v154
	v_pk_fma_f16 v125, v125, v132, v155
	v_pk_fma_f16 v124, v124, v133, v156
	v_dot2_f32_f16 v158, v127, v146, 0
	v_dot2_f32_f16 v158, v126, v147, v158
	v_dot2_f32_f16 v158, v125, v148, v158
	v_dot2_f32_f16 v158, v124, v149, v158
	s_waitcnt lgkmcnt(0)
	v_dot2_f32_f16 v151, v127, v72, 0
	v_dot2_f32_f16 v151, v126, v73, v151
	v_dot2_f32_f16 v151, v125, v74, v151
	v_dot2_f32_f16 v151, v124, v75, v151
	ds_read_b128 v[134:137], v114 offset:42368
	ds_read_b128 v[138:141], v114 offset:46464
	ds_read_b128 v[142:145], v114 offset:50560
	v_add_f32_dpp v151, v151, v151 quad_perm:[1,0,3,2] row_mask:0xf bank_mask:0xf bound_ctrl:1
	ds_read_b128 v[130:133], v114 offset:30080
	ds_read_b128 v[146:149], v114 offset:54656
	v_add_f32_dpp v151, v151, v151 quad_perm:[2,3,0,1] row_mask:0xf bank_mask:0xf bound_ctrl:1
	ds_read_b32 v160, v115 offset:2304
	ds_write_b32 v116, v158 offset:14336
	v_add_f32_dpp v151, v151, v151 row_half_mirror row_mask:0xf bank_mask:0xf bound_ctrl:1
	v_cvt_pkrtz_f16_f32 v152, -v151, -v151
	v_pk_mul_f16 v153, v152, v68
	v_pk_mul_f16 v154, v152, v69
	v_pk_mul_f16 v155, v152, v70
	v_pk_mul_f16 v156, v152, v71
	v_pk_fma_f16 v153, v85, v64, v153
	v_pk_fma_f16 v154, v85, v65, v154
	v_pk_fma_f16 v155, v85, v66, v155
	v_pk_fma_f16 v156, v85, v67, v156
	v_pk_fma_f16 v127, v127, v60, v153
	v_pk_fma_f16 v126, v126, v61, v154
	v_pk_fma_f16 v125, v125, v62, v155
	v_pk_fma_f16 v124, v124, v63, v156
	v_dot2_f32_f16 v157, v127, v56, 0
	v_dot2_f32_f16 v157, v126, v57, v157
	v_dot2_f32_f16 v157, v125, v58, v157
	v_dot2_f32_f16 v157, v124, v59, v157
	s_waitcnt lgkmcnt(0)
	v_dot2_f32_f16 v151, v127, v134, 0
	v_dot2_f32_f16 v151, v126, v135, v151
	v_dot2_f32_f16 v151, v125, v136, v151
	v_dot2_f32_f16 v151, v124, v137, v151
	ds_read_b128 v[72:75], v114 offset:42496
	ds_read_b128 v[68:71], v114 offset:46592
	ds_read_b128 v[64:67], v114 offset:50688
	v_add_f32_dpp v151, v151, v151 quad_perm:[1,0,3,2] row_mask:0xf bank_mask:0xf bound_ctrl:1
	ds_read_b128 v[60:63], v114 offset:30208
	ds_read_b128 v[56:59], v114 offset:54784
	v_add_f32_dpp v151, v151, v151 quad_perm:[2,3,0,1] row_mask:0xf bank_mask:0xf bound_ctrl:1
	ds_read_b32 v85, v115 offset:2560
	ds_write_b32 v116, v157 offset:16384
	v_add_f32_dpp v151, v151, v151 row_half_mirror row_mask:0xf bank_mask:0xf bound_ctrl:1
	v_cvt_pkrtz_f16_f32 v152, -v151, -v151
	v_pk_mul_f16 v153, v152, v138
	v_pk_mul_f16 v154, v152, v139
	v_pk_mul_f16 v155, v152, v140
	v_pk_mul_f16 v156, v152, v141
	v_pk_fma_f16 v153, v160, v142, v153
	v_pk_fma_f16 v154, v160, v143, v154
	v_pk_fma_f16 v155, v160, v144, v155
	v_pk_fma_f16 v156, v160, v145, v156
	v_pk_fma_f16 v127, v127, v130, v153
	v_pk_fma_f16 v126, v126, v131, v154
	v_pk_fma_f16 v125, v125, v132, v155
	v_pk_fma_f16 v124, v124, v133, v156
	v_dot2_f32_f16 v158, v127, v146, 0
	v_dot2_f32_f16 v158, v126, v147, v158
	v_dot2_f32_f16 v158, v125, v148, v158
	v_dot2_f32_f16 v158, v124, v149, v158
	s_waitcnt lgkmcnt(0)
	v_dot2_f32_f16 v151, v127, v72, 0
	v_dot2_f32_f16 v151, v126, v73, v151
	v_dot2_f32_f16 v151, v125, v74, v151
	v_dot2_f32_f16 v151, v124, v75, v151
	ds_read_b128 v[134:137], v114 offset:42624
	ds_read_b128 v[138:141], v114 offset:46720
	ds_read_b128 v[142:145], v114 offset:50816
	v_add_f32_dpp v151, v151, v151 quad_perm:[1,0,3,2] row_mask:0xf bank_mask:0xf bound_ctrl:1
	ds_read_b128 v[130:133], v114 offset:30336
	ds_read_b128 v[146:149], v114 offset:54912
	v_add_f32_dpp v151, v151, v151 quad_perm:[2,3,0,1] row_mask:0xf bank_mask:0xf bound_ctrl:1
	ds_read_b32 v160, v115 offset:2816
	ds_write_b32 v116, v158 offset:18432
	v_add_f32_dpp v151, v151, v151 row_half_mirror row_mask:0xf bank_mask:0xf bound_ctrl:1
	v_cvt_pkrtz_f16_f32 v152, -v151, -v151
	v_pk_mul_f16 v153, v152, v68
	v_pk_mul_f16 v154, v152, v69
	v_pk_mul_f16 v155, v152, v70
	v_pk_mul_f16 v156, v152, v71
	v_pk_fma_f16 v153, v85, v64, v153
	v_pk_fma_f16 v154, v85, v65, v154
	v_pk_fma_f16 v155, v85, v66, v155
	v_pk_fma_f16 v156, v85, v67, v156
	v_pk_fma_f16 v127, v127, v60, v153
	v_pk_fma_f16 v126, v126, v61, v154
	v_pk_fma_f16 v125, v125, v62, v155
	v_pk_fma_f16 v124, v124, v63, v156
	v_dot2_f32_f16 v157, v127, v56, 0
	v_dot2_f32_f16 v157, v126, v57, v157
	v_dot2_f32_f16 v157, v125, v58, v157
	v_dot2_f32_f16 v157, v124, v59, v157
	s_waitcnt lgkmcnt(0)
	v_dot2_f32_f16 v151, v127, v134, 0
	v_dot2_f32_f16 v151, v126, v135, v151
	v_dot2_f32_f16 v151, v125, v136, v151
	v_dot2_f32_f16 v151, v124, v137, v151
	ds_read_b128 v[72:75], v114 offset:42752
	ds_read_b128 v[68:71], v114 offset:46848
	ds_read_b128 v[64:67], v114 offset:50944
	v_add_f32_dpp v151, v151, v151 quad_perm:[1,0,3,2] row_mask:0xf bank_mask:0xf bound_ctrl:1
	ds_read_b128 v[60:63], v114 offset:30464
	ds_read_b128 v[56:59], v114 offset:55040
	v_add_f32_dpp v151, v151, v151 quad_perm:[2,3,0,1] row_mask:0xf bank_mask:0xf bound_ctrl:1
	ds_read_b32 v85, v115 offset:3072
	ds_write_b32 v116, v157 offset:20480
	v_add_f32_dpp v151, v151, v151 row_half_mirror row_mask:0xf bank_mask:0xf bound_ctrl:1
	v_cvt_pkrtz_f16_f32 v152, -v151, -v151
	v_pk_mul_f16 v153, v152, v138
	v_pk_mul_f16 v154, v152, v139
	v_pk_mul_f16 v155, v152, v140
	v_pk_mul_f16 v156, v152, v141
	v_pk_fma_f16 v153, v160, v142, v153
	v_pk_fma_f16 v154, v160, v143, v154
	v_pk_fma_f16 v155, v160, v144, v155
	v_pk_fma_f16 v156, v160, v145, v156
	v_pk_fma_f16 v127, v127, v130, v153
	v_pk_fma_f16 v126, v126, v131, v154
	v_pk_fma_f16 v125, v125, v132, v155
	v_pk_fma_f16 v124, v124, v133, v156
	v_dot2_f32_f16 v158, v127, v146, 0
	v_dot2_f32_f16 v158, v126, v147, v158
	v_dot2_f32_f16 v158, v125, v148, v158
	v_dot2_f32_f16 v158, v124, v149, v158
	s_waitcnt lgkmcnt(0)
	v_dot2_f32_f16 v151, v127, v72, 0
	v_dot2_f32_f16 v151, v126, v73, v151
	v_dot2_f32_f16 v151, v125, v74, v151
	v_dot2_f32_f16 v151, v124, v75, v151
	ds_read_b128 v[134:137], v114 offset:42880
	ds_read_b128 v[138:141], v114 offset:46976
	ds_read_b128 v[142:145], v114 offset:51072
	v_add_f32_dpp v151, v151, v151 quad_perm:[1,0,3,2] row_mask:0xf bank_mask:0xf bound_ctrl:1
	ds_read_b128 v[130:133], v114 offset:30592
	ds_read_b128 v[146:149], v114 offset:55168
	v_add_f32_dpp v151, v151, v151 quad_perm:[2,3,0,1] row_mask:0xf bank_mask:0xf bound_ctrl:1
	ds_read_b32 v160, v115 offset:3328
	ds_write_b32 v116, v158 offset:22528
	v_add_f32_dpp v151, v151, v151 row_half_mirror row_mask:0xf bank_mask:0xf bound_ctrl:1
	v_cvt_pkrtz_f16_f32 v152, -v151, -v151
	v_pk_mul_f16 v153, v152, v68
	v_pk_mul_f16 v154, v152, v69
	v_pk_mul_f16 v155, v152, v70
	v_pk_mul_f16 v156, v152, v71
	v_pk_fma_f16 v153, v85, v64, v153
	v_pk_fma_f16 v154, v85, v65, v154
	v_pk_fma_f16 v155, v85, v66, v155
	v_pk_fma_f16 v156, v85, v67, v156
	v_pk_fma_f16 v127, v127, v60, v153
	v_pk_fma_f16 v126, v126, v61, v154
	v_pk_fma_f16 v125, v125, v62, v155
	v_pk_fma_f16 v124, v124, v63, v156
	v_dot2_f32_f16 v157, v127, v56, 0
	v_dot2_f32_f16 v157, v126, v57, v157
	v_dot2_f32_f16 v157, v125, v58, v157
	v_dot2_f32_f16 v157, v124, v59, v157
	s_waitcnt lgkmcnt(0)
	v_dot2_f32_f16 v151, v127, v134, 0
	v_dot2_f32_f16 v151, v126, v135, v151
	v_dot2_f32_f16 v151, v125, v136, v151
	v_dot2_f32_f16 v151, v124, v137, v151
	ds_read_b128 v[72:75], v114 offset:43008
	ds_read_b128 v[68:71], v114 offset:47104
	ds_read_b128 v[64:67], v114 offset:51200
	v_add_f32_dpp v151, v151, v151 quad_perm:[1,0,3,2] row_mask:0xf bank_mask:0xf bound_ctrl:1
	ds_read_b128 v[60:63], v114 offset:30720
	ds_read_b128 v[56:59], v114 offset:55296
	v_add_f32_dpp v151, v151, v151 quad_perm:[2,3,0,1] row_mask:0xf bank_mask:0xf bound_ctrl:1
	ds_read_b32 v85, v115 offset:3584
	ds_write_b32 v116, v157 offset:24576
	v_add_f32_dpp v151, v151, v151 row_half_mirror row_mask:0xf bank_mask:0xf bound_ctrl:1
	v_cvt_pkrtz_f16_f32 v152, -v151, -v151
	v_pk_mul_f16 v153, v152, v138
	v_pk_mul_f16 v154, v152, v139
	v_pk_mul_f16 v155, v152, v140
	v_pk_mul_f16 v156, v152, v141
	v_pk_fma_f16 v153, v160, v142, v153
	v_pk_fma_f16 v154, v160, v143, v154
	v_pk_fma_f16 v155, v160, v144, v155
	v_pk_fma_f16 v156, v160, v145, v156
	v_pk_fma_f16 v127, v127, v130, v153
	v_pk_fma_f16 v126, v126, v131, v154
	v_pk_fma_f16 v125, v125, v132, v155
	v_pk_fma_f16 v124, v124, v133, v156
	v_dot2_f32_f16 v158, v127, v146, 0
	v_dot2_f32_f16 v158, v126, v147, v158
	v_dot2_f32_f16 v158, v125, v148, v158
	v_dot2_f32_f16 v158, v124, v149, v158
	s_waitcnt lgkmcnt(0)
	v_dot2_f32_f16 v151, v127, v72, 0
	v_dot2_f32_f16 v151, v126, v73, v151
	v_dot2_f32_f16 v151, v125, v74, v151
	v_dot2_f32_f16 v151, v124, v75, v151
	ds_read_b128 v[134:137], v114 offset:43136
	ds_read_b128 v[138:141], v114 offset:47232
	ds_read_b128 v[142:145], v114 offset:51328
	v_add_f32_dpp v151, v151, v151 quad_perm:[1,0,3,2] row_mask:0xf bank_mask:0xf bound_ctrl:1
	ds_read_b128 v[130:133], v114 offset:30848
	ds_read_b128 v[146:149], v114 offset:55424
	v_add_f32_dpp v151, v151, v151 quad_perm:[2,3,0,1] row_mask:0xf bank_mask:0xf bound_ctrl:1
	ds_read_b32 v160, v115 offset:3840
	ds_write_b32 v116, v158 offset:26624
	v_add_f32_dpp v151, v151, v151 row_half_mirror row_mask:0xf bank_mask:0xf bound_ctrl:1
	v_cvt_pkrtz_f16_f32 v152, -v151, -v151
	v_pk_mul_f16 v153, v152, v68
	v_pk_mul_f16 v154, v152, v69
	v_pk_mul_f16 v155, v152, v70
	v_pk_mul_f16 v156, v152, v71
	v_pk_fma_f16 v153, v85, v64, v153
	v_pk_fma_f16 v154, v85, v65, v154
	v_pk_fma_f16 v155, v85, v66, v155
	v_pk_fma_f16 v156, v85, v67, v156
	v_pk_fma_f16 v127, v127, v60, v153
	v_pk_fma_f16 v126, v126, v61, v154
	v_pk_fma_f16 v125, v125, v62, v155
	v_pk_fma_f16 v124, v124, v63, v156
	v_dot2_f32_f16 v157, v127, v56, 0
	v_dot2_f32_f16 v157, v126, v57, v157
	v_dot2_f32_f16 v157, v125, v58, v157
	v_dot2_f32_f16 v157, v124, v59, v157
	s_waitcnt lgkmcnt(0)
	v_dot2_f32_f16 v151, v127, v134, 0
	v_dot2_f32_f16 v151, v126, v135, v151
	v_dot2_f32_f16 v151, v125, v136, v151
	v_dot2_f32_f16 v151, v124, v137, v151
	s_nop 2
	v_add_f32_dpp v151, v151, v151 quad_perm:[1,0,3,2] row_mask:0xf bank_mask:0xf bound_ctrl:1
	s_nop 1
	v_add_f32_dpp v151, v151, v151 quad_perm:[2,3,0,1] row_mask:0xf bank_mask:0xf bound_ctrl:1
	s_nop 0
	ds_write_b32 v116, v157 offset:28672
	v_add_f32_dpp v151, v151, v151 row_half_mirror row_mask:0xf bank_mask:0xf bound_ctrl:1
	v_cvt_pkrtz_f16_f32 v152, -v151, -v151
	v_pk_mul_f16 v153, v152, v138
	v_pk_mul_f16 v154, v152, v139
	v_pk_mul_f16 v155, v152, v140
	v_pk_mul_f16 v156, v152, v141
	v_pk_fma_f16 v153, v160, v142, v153
	v_pk_fma_f16 v154, v160, v143, v154
	v_pk_fma_f16 v155, v160, v144, v155
	v_pk_fma_f16 v156, v160, v145, v156
	v_pk_fma_f16 v127, v127, v130, v153
	v_pk_fma_f16 v126, v126, v131, v154
	v_pk_fma_f16 v125, v125, v132, v155
	v_pk_fma_f16 v124, v124, v133, v156
	v_dot2_f32_f16 v158, v127, v146, 0
	v_dot2_f32_f16 v158, v126, v147, v158
	v_dot2_f32_f16 v158, v125, v148, v158
	v_dot2_f32_f16 v158, v124, v149, v158
	s_nop 2
	ds_write_b32 v116, v158 offset:30720
	s_waitcnt lgkmcnt(0)
	s_barrier
	s_waitcnt lgkmcnt(1)
	ds_read_b128 v[56:59], v94 offset:57856
	ds_read_b128 v[60:63], v94 offset:57872
	ds_read_b128 v[64:67], v94 offset:57888
	ds_read_b128 v[68:71], v94 offset:57904
	s_waitcnt lgkmcnt(3)
	v_add_f32_e32 v56, v56, v57
	v_add_f32_e32 v57, v58, v59
	v_add_f32_e32 v56, v56, v57
	s_waitcnt lgkmcnt(2)
	v_add_f32_e32 v57, v60, v61
	v_add_f32_e32 v58, v62, v63
	v_add_f32_e32 v57, v57, v58
	v_add_f32_e32 v56, v56, v57
	s_waitcnt lgkmcnt(1)
	v_add_f32_e32 v57, v64, v65
	v_add_f32_e32 v58, v66, v67
	v_add_f32_e32 v57, v57, v58
	s_waitcnt lgkmcnt(0)
	v_add_f32_e32 v58, v68, v69
	v_add_f32_e32 v59, v70, v71
	v_add_f32_e32 v58, v58, v59
	v_add_f32_e32 v57, v57, v58
	v_add_f32_e32 v58, v56, v57
	s_nop 1
	v_add_f32_dpp v58, v58, v58 quad_perm:[1,0,3,2] row_mask:0xf bank_mask:0xf bound_ctrl:1
	s_nop 1
	v_add_f32_dpp v58, v58, v58 quad_perm:[2,3,0,1] row_mask:0xf bank_mask:0xf bound_ctrl:1
	s_nop 1
	v_add_f32_dpp v58, v58, v58 row_half_mirror row_mask:0xf bank_mask:0xf bound_ctrl:1
	s_nop 1
	v_add_f32_dpp v58, v58, v58 row_mirror row_mask:0xf bank_mask:0xf bound_ctrl:1
	s_nop 0
	v_readlane_b32 s19, v58, 16
	v_readlane_b32 s23, v58, 48
	v_readlane_b32 s18, v58, 0
	v_readlane_b32 s22, v58, 32
	v_mov_b32_e32 v58, s19
	v_mov_b32_e32 v59, s23
	v_add_f32_e32 v58, s18, v58
	v_add_f32_e32 v59, s22, v59
	v_cndmask_b32_e64 v58, v59, v58, s[12:13]
	v_fmac_f32_e32 v57, 0xbc800000, v58
	v_fmac_f32_e32 v56, 0xbc800000, v58
	v_mul_f32_e32 v58, v57, v57
	v_fmac_f32_e32 v58, v56, v56
	s_nop 1
	v_add_f32_dpp v58, v58, v58 quad_perm:[1,0,3,2] row_mask:0xf bank_mask:0xf bound_ctrl:1
	s_nop 1
	v_add_f32_dpp v58, v58, v58 quad_perm:[2,3,0,1] row_mask:0xf bank_mask:0xf bound_ctrl:1
	s_nop 1
	v_add_f32_dpp v58, v58, v58 row_half_mirror row_mask:0xf bank_mask:0xf bound_ctrl:1
	s_nop 1
	v_add_f32_dpp v58, v58, v58 row_mirror row_mask:0xf bank_mask:0xf bound_ctrl:1
	s_nop 0
	v_readlane_b32 s22, v58, 0
	v_readlane_b32 s24, v58, 16
	v_readlane_b32 s23, v58, 32
	v_readlane_b32 s25, v58, 48
	s_and_saveexec_b64 s[18:19], s[16:17]
	s_cbranch_execz .LBB0_1242
	v_mov_b32_e32 v58, s24
	v_mov_b32_e32 v59, s25
	v_add_f32_e32 v58, s22, v58
	v_add_f32_e32 v59, s23, v59
	v_cndmask_b32_e64 v58, v59, v58, s[12:13]
	v_fmamk_f32 v58, v58, 0x3c800000, v120
	v_mul_f32_e32 v59, 0x4b800000, v58
	v_cmp_gt_f32_e32 vcc, s29, v58
	s_nop 1
	v_cndmask_b32_e32 v58, v58, v59, vcc
	v_rsq_f32_e32 v60, v58
	ds_read_b64 v[58:59], v110 offset:512
	ds_read_b32 v105, v123 offset:57600
	ds_read_b64 v[62:63], v121 offset:37120
	v_mul_f32_e32 v61, 0x45800000, v60
	v_cndmask_b32_e32 v64, v60, v61, vcc
	v_mul_f32_e32 v60, v57, v64
	s_waitcnt lgkmcnt(2)
	v_mov_b32_e32 v61, v59
	s_waitcnt lgkmcnt(1)
	v_pk_mul_f32 v[60:61], v[104:105], v[60:61]
	v_mul_f32_e32 v56, v56, v64
	v_add_f32_e32 v57, v87, v60
	v_add_f32_e32 v57, v57, v61
	s_waitcnt lgkmcnt(0)
	v_mul_f32_e32 v59, v63, v57
	v_mov_b32_e32 v85, v105
	v_mov_b32_e32 v57, v58
	v_pk_mul_f32 v[56:57], v[84:85], v[56:57]
	s_nop 0
	v_add_f32_e32 v56, v86, v56
	v_add_f32_e32 v56, v56, v57
	v_mul_f32_e32 v56, v62, v56
	v_cvt_pk_bf16_f32 v58, v56, v59
	v_lshl_add_u32 v56, s4, 4, v95
	v_ashrrev_i32_e32 v57, 31, v56
	v_lshlrev_b64 v[56:57], 12, v[56:57]
	v_lshl_add_u64 v[56:57], v[106:107], 0, v[56:57]
	global_store_dword v[56:57], v58, off offset:2048
